# start-up hand-off made asynchronous: flag load issued after the w_in conversion, checked after the x-loop where the census atomic is posted without waiting; end of P0 only stores the returned rank (on
# speedup vs baseline: 1.0047x; 1.0047x over previous
; #define LAS __attribute__((address_space(3)))
; __device__ __forceinline__ unsigned xb_add(unsigned* p, unsigned v) { return __hip_atomic_fetch_add(p, v, __ATOMIC_RELAXED, __HIP_MEMORY_SCOPE_AGENT); }
; __device__ __forceinline__ unsigned xb_xcc_id() { return (unsigned)__builtin_amdgcn_s_getreg((3 << 11) | 20) & 0xFu; }
; __global__ void __launch_bounds__(NT, 2) fwd_mega(Args A) {
;     ...
;     grid.sync();
;     XcdBarrier xbar; xbar.bar = barw; xbar.x = xb_xcc_id(); xbar.st = (volatile LAS unsigned*)(lds + LDS_BARST);
;     if (tid == 0) ((LAS unsigned*)(lds + LDS_BARST))[2] = xb_add(&barw[XB_XCNT(xbar.x)], 1u);
;     ...
;         for (int m = gw; m < T; m += NGW) {
;             const float* xrow = (m < 8192) ? A.xp + (size_t)m * D : A.xs + (size_t)(m - 8192) * D;
;             const f32x4* xr = (const f32x4*)xrow + lane; f32x4 v[8]; float s = 0.f;
; #pragma unroll
;             for (int j = 0; j < 8; ++j) { v[j] = __builtin_nontemporal_load(xr + 64 * j); s += (v[j][0] * v[j][0] + v[j][1] * v[j][1]) + (v[j][2] * v[j][2] + v[j][3] * v[j][3]); }
;             s = wave_sum(s);
;             if (lane == 0) r1[m] = 1.0f / sqrtf(s * (1.0f / D) + pg8::EPSN);
.Lcva_fin:
.Lcva_end:
.LBB0_59:
	v_cmp_eq_u32_e64 s[86:87], 0, v160
	v_mov_b32_e32 v245, 0
	v_mov_b32_e32 v247, 0x10000
	s_and_saveexec_b64 s[84:85], s[86:87]
	global_load_dword v245, v247, s[34:35] sc1
	s_or_b64 exec, exec, s[84:85]
	s_cmpk_gt_i32 s58, 0x3fff
	v_mbcnt_lo_u32_b32 v161, -1, 0
	s_cbranch_scc1 .LBB0_64
	v_mbcnt_hi_u32_b32 v0, -1, v161
	v_and_b32_e32 v1, 64, v0
	v_add_u32_e32 v1, 64, v1
	v_xor_b32_e32 v2, 1, v0
	v_cmp_lt_i32_e32 vcc, v2, v1
	s_ashr_i32 s59, s58, 31
	s_lshl_b64 s[0:1], s[58:59], 12
	v_cndmask_b32_e32 v2, v0, v2, vcc
	v_lshlrev_b32_e32 v36, 2, v2
	v_xor_b32_e32 v2, 2, v0
	v_cmp_lt_i32_e32 vcc, v2, v1
	s_ashr_i32 s53, s52, 31
	v_lshl_or_b32 v34, v152, 3, s0
	v_cndmask_b32_e32 v2, v0, v2, vcc
	v_lshlrev_b32_e32 v37, 2, v2
	v_xor_b32_e32 v2, 4, v0
	v_cmp_lt_i32_e32 vcc, v2, v1
	v_mov_b32_e32 v35, s1
	s_lshl_b64 s[40:41], s[52:53], 12
	v_cndmask_b32_e32 v2, v0, v2, vcc
	v_lshlrev_b32_e32 v38, 2, v2
	v_xor_b32_e32 v2, 8, v0
	v_cmp_lt_i32_e32 vcc, v2, v1
	s_lshl_b64 s[0:1], s[58:59], 2
	s_add_u32 s0, s0, 0x30000
	v_cndmask_b32_e32 v2, v0, v2, vcc
	v_lshlrev_b32_e32 v39, 2, v2
	v_xor_b32_e32 v2, 16, v0
	v_cmp_lt_i32_e32 vcc, v2, v1
	v_mov_b32_e32 v33, 0
	v_cmp_eq_u32_e64 s[4:5], 0, v152
	v_cndmask_b32_e32 v2, v0, v2, vcc
	v_lshlrev_b32_e32 v40, 2, v2
	v_xor_b32_e32 v2, 32, v0
	v_cmp_lt_i32_e32 vcc, v2, v1
	s_addc_u32 s1, s1, 0
	s_lshl_b64 s[42:43], s[52:53], 2
	v_cndmask_b32_e32 v0, v0, v2, vcc
	v_lshlrev_b32_e32 v41, 2, v0
	v_lshlrev_b32_e32 v32, 4, v152
	s_movk_i32 s62, 0x1000
	v_mov_b32_e32 v42, 0x358637bd
	s_mov_b32 s63, 0xf800000
	v_mov_b32_e32 v43, 0x260
	s_branch .LBB0_62

; #define LAS __attribute__((address_space(3)))
; __device__ __forceinline__ unsigned f2bf(float f) { unsigned u = __builtin_bit_cast(unsigned, f); return (u + 0x7fffu + ((u >> 16) & 1u)) >> 16; }
; __device__ __forceinline__ unsigned xb_add(unsigned* p, unsigned v) { return __hip_atomic_fetch_add(p, v, __ATOMIC_RELAXED, __HIP_MEMORY_SCOPE_AGENT); }
; __global__ void __launch_bounds__(NT, 2) fwd_mega(Args A) {
;     ...
;     if (tid == 0) ((LAS unsigned*)(lds + LDS_BARST))[2] = xb_add(&barw[XB_XCNT(xbar.x)], 1u);
;     ...
;         const int gt = vcu * NT + tid, NGT = G * NT;
;         for (int i = gt; i < 8 * 128 * 128; i += NGT) ((bf16*)(ws + WS_WSP))[i] = (bf16)f2bf(A.w_sp[i]);
.LBB0_64:
	s_and_saveexec_b64 s[84:85], s[86:87]
	s_cbranch_execz .Lgq_done
	s_mov_b32 s82, 0x7a3c59e1
	v_cmp_ne_u32_e32 vcc, s82, v245
	s_cbranch_vccz .Lgq_ok
	s_mov_b32 s83, 0
.Lgq_spin:
	global_load_dword v245, v247, s[34:35] sc1
	s_waitcnt vmcnt(0)
	v_cmp_ne_u32_e32 vcc, s82, v245
	s_cbranch_vccz .Lgq_ok
	s_sleep 2
	s_add_i32 s83, s83, 1
	s_cmp_lt_u32 s83, 0x100000
	s_cbranch_scc1 .Lgq_spin
.Lgq_ok:
	buffer_inv sc1
	s_lshl_b32 s82, s33, 8
	v_mov_b32_e32 v247, s82
	v_mov_b32_e32 v248, 1
	global_atomic_add v246, v247, v248, s[34:35] offset:1024 sc0
.Lgq_done:
	s_or_b64 exec, exec, s[84:85]
	s_lshl_b32 s6, s30, 9
	v_cvt_f32_u32_e32 v1, s6
	v_lshl_add_u32 v0, s3, 9, v160
	s_mov_b32 s0, 0x20000
	v_cmp_gt_i32_e32 vcc, s0, v0
	v_rcp_iflag_f32_e32 v8, v1
	v_add_u32_e32 v1, s6, v0
	s_and_saveexec_b64 s[36:37], vcc
	s_cbranch_execz .LBB0_72
	v_mul_f32_e32 v4, 0x4f7ffffe, v8
	v_cvt_u32_f32_e32 v4, v4
	v_mov_b32_e32 v3, s6
	v_cmp_gt_i32_e32 vcc, s0, v1
	v_max_i32_e32 v2, 0x20000, v1
	s_sub_i32 s0, 0, s6
	v_addc_co_u32_e64 v3, s[4:5], v0, v3, vcc
	v_sub_u32_e32 v2, v2, v3
	v_mul_lo_u32 v3, s0, v4
	v_mul_hi_u32 v3, v4, v3
	v_add_u32_e32 v3, v4, v3
	v_mul_hi_u32 v3, v2, v3
	v_mul_lo_u32 v4, v3, s6
	v_sub_u32_e32 v2, v2, v4
	v_add_u32_e32 v4, 1, v3
	v_cmp_le_u32_e64 s[4:5], s6, v2
	s_mov_b64 s[38:39], -1
	s_nop 0
	v_cndmask_b32_e64 v3, v3, v4, s[4:5]
	v_subrev_u32_e32 v4, s6, v2
	v_cndmask_b32_e64 v2, v2, v4, s[4:5]
	v_add_u32_e32 v4, 1, v3
	v_cmp_le_u32_e64 s[4:5], s6, v2
	s_nop 1
	v_cndmask_b32_e64 v2, v3, v4, s[4:5]
	v_addc_co_u32_e32 v4, vcc, 1, v2, vcc
	v_cmp_lt_u32_e32 vcc, 1, v4
	v_mov_b32_e32 v2, v0
	s_and_saveexec_b64 s[4:5], vcc
	s_cbranch_execz .LBB0_69
	s_add_u32 s38, s28, 0x1c0000
	s_addc_u32 s39, s29, 0
	v_and_b32_e32 v5, -2, v4
	s_lshl_b32 s0, s30, 10
	s_mov_b32 s1, s0
	s_mov_b64 s[40:41], 0
	s_movk_i32 s3, 0x7fff
	v_mov_b32_e32 v6, 1
	v_mov_b32_e32 v7, v5
	v_mov_b64_e32 v[2:3], v[0:1]

; #define LAS __attribute__((address_space(3)))
; __device__ __forceinline__ unsigned xb_add(unsigned* p, unsigned v) { return __hip_atomic_fetch_add(p, v, __ATOMIC_RELAXED, __HIP_MEMORY_SCOPE_AGENT); }
; __device__ __forceinline__ unsigned xb_xcc_id() { return (unsigned)__builtin_amdgcn_s_getreg((3 << 11) | 20) & 0xFu; }
; __global__ void __launch_bounds__(NT, 2) fwd_mega(Args A) {
;     ...
;     grid.sync();
;     XcdBarrier xbar; xbar.bar = barw; xbar.x = xb_xcc_id(); xbar.st = (volatile LAS unsigned*)(lds + LDS_BARST);
;     if (tid == 0) ((LAS unsigned*)(lds + LDS_BARST))[2] = xb_add(&barw[XB_XCNT(xbar.x)], 1u);
.LBB0_111:
	s_or_b64 exec, exec, s[8:9]
	s_and_saveexec_b64 s[4:5], s[88:89]
	s_cbranch_execz .Lcs_done
	s_waitcnt vmcnt(0)
	v_mov_b32_e32 v0, 0x23fc8
	ds_write_b32 v0, v246
